# DA main loop key permutation (conflict-free V/K LDS reads) on top of v15
# baseline (speedup 1.0000x reference)
; #define LAS __attribute__((address_space(3)))
; DI void da_unit(const Params& p, lds8* lds, int bl, int hd, int qb, float lam) {
;     ...
;   bf16_t* QDA = (bf16_t*)(ws + OFF_QDA); const bf16_t* KDA = (const bf16_t*)(ws + OFF_KDA); const bf16_t* VDA = (const bf16_t*)(ws + OFF_VDA);
;   const int r = lane & 31, h = lane >> 5, qs = wid & 3, c = wid >> 2;
;   const size_t rowbase = (size_t)bl * SEQ; const int q0 = qb * 128; const int qpos = q0 + 32 * qs + r;
;   bf16x8 q[4];
;   { const bf16_t* qp = QDA + (rowbase + qpos) * DM + hd * 128 + c * 64 + 8 * h;
; #pragma unroll
;     for (int ks = 0; ks < 4; ++ks) q[ks] = *(const bf16x8*)(qp + 16 * ks); }
;   const int nt = 2 * (qb + 1);
;   DaCtx cx;
;   { const int ch0 = tid, ch1 = tid + 512; cx.sr0 = ch0 >> 4; cx.sc0 = ch0 & 15; cx.sr1 = ch1 >> 4; cx.sc1 = ch1 & 15; }
;   cx.kg = KDA + rowbase * DM + hd * 128; cx.vg = VDA + rowbase * DM + hd * 128;
;   cx.koff = r * DA_KSTR + h * 16 + c * 128;
;   cx.voff = 64 * DA_KSTR + (4 * h + ((lane & 15) >> 2)) * DA_KSTR + ((lane >> 4) & 1) * 32 + (lane & 3) * 8;
;   cx.qpos = qpos; cx.h = h; cx.qs = qs; cx.q0 = q0;
; #pragma unroll
;   for (int t0 = 0; t0 < 2; ++t0) { const size_t ro = (size_t)t0 * 64; lds8* b = lds + t0 * DA_STAGE;
;     const u32x4 kr0 = *(const u32x4*)(cx.kg + (ro + cx.sr0) * DM + cx.sc0 * 8), kr1 = *(const u32x4*)(cx.kg + (ro + cx.sr1) * DM + cx.sc1 * 8);
;     const u32x4 vr0 = *(const u32x4*)(cx.vg + (ro + cx.sr0) * DM + cx.sc0 * 8), vr1 = *(const u32x4*)(cx.vg + (ro + cx.sr1) * DM + cx.sc1 * 8);
;     *(LAS u32x4*)(b + cx.sr0 * DA_KSTR + cx.sc0 * 16) = kr0; *(LAS u32x4*)(b + cx.sr1 * DA_KSTR + cx.sc1 * 16) = kr1;
;     *(LAS u32x4*)(b + 64 * DA_KSTR + cx.sr0 * DA_KSTR + cx.sc0 * 16) = vr0; *(LAS u32x4*)(b + 64 * DA_KSTR + cx.sr1 * DA_KSTR + cx.sc1 * 16) = vr1; }
;   __syncthreads();
.LBB0_845:
	s_or_b64 exec, exec, s[10:11]
	v_mov_b32_e32 v134, v200
	s_ashr_i32 s6, s20, 7
	s_sub_i32 s12, 15, s6
	v_readfirstlane_b32 s16, v134
	s_bfe_u32 s14, s16, 0x20006
	s_lshl_b32 s1, s12, 7
	s_lshl_b32 s3, s14, 5
	s_bfe_u32 s13, s20, 0x40003
	v_and_b32_e32 v179, 31, v134
	s_or_b32 s18, s3, s1
	s_lshl_b32 s0, s13, 11
	v_or_b32_e32 v183, s18, v179
	v_add_u32_e32 v186, s0, v183
	v_readlane_b32 s10, v254, 43
	v_lshlrev_b64 v[0:1], 11, v[186:187]
	v_readlane_b32 s11, v254, 44
	s_ashr_i32 s17, s16, 8
	v_bfe_u32 v135, v134, 5, 1
	v_lshl_add_u64 v[0:1], s[10:11], 0, v[0:1]
	s_lshl_b32 s10, s20, 7
	s_and_b32 s15, s10, 0x380
	s_lshl_b32 s88, s15, 1
	s_lshl_b32 s10, s17, 6
	v_lshl_add_u64 v[0:1], v[0:1], 0, s[88:89]
	s_ashr_i32 s11, s10, 31
	v_lshl_add_u64 v[2:3], s[10:11], 1, v[0:1]
	s_lshl_b32 s10, s13, 22
	v_readlane_b32 s2, v254, 45
	v_lshlrev_b32_e32 v0, 4, v135
	v_mov_b32_e32 v1, v187
	s_add_u32 s11, s2, s10
	v_readlane_b32 s2, v254, 46
	v_lshl_add_u64 v[2:3], v[2:3], 0, v[0:1]
	s_addc_u32 s13, s2, 0
	global_load_dwordx4 v[172:175], v[2:3], off
	global_load_dwordx4 v[168:171], v[2:3], off offset:32
	global_load_dwordx4 v[164:167], v[2:3], off offset:64
	global_load_dwordx4 v[160:163], v[2:3], off offset:96
	s_add_u32 s22, s11, s88
	v_lshlrev_b32_e32 v3, 1, v134
	v_ashrrev_i32_e32 v2, 4, v134
	v_and_b32_e32 v136, 15, v134
	s_addc_u32 s23, s13, 0
	v_readlane_b32 s2, v254, 47
	v_and_b32_e32 v100, 32, v3
	v_lshlrev_b32_e32 v3, 3, v134
	v_add_u32_e32 v1, 0x200, v134
	s_add_u32 s10, s2, s10
	v_readlane_b32 s2, v254, 48
	v_and_b32_e32 v101, 24, v3
	v_ashrrev_i32_e32 v3, 31, v2
	v_lshlrev_b32_e32 v186, 4, v136
	v_ashrrev_i32_e32 v4, 4, v1
	s_addc_u32 s11, s2, 0
	v_lshl_add_u64 v[6:7], s[22:23], 0, v[186:187]
	v_lshlrev_b64 v[96:97], 11, v[2:3]
	s_add_u32 s24, s10, s88
	v_ashrrev_i32_e32 v5, 31, v4
	v_lshl_add_u64 v[8:9], v[6:7], 0, v[96:97]
	s_addc_u32 s25, s11, 0
	global_load_dwordx4 v[10:13], v[8:9], off
	v_lshlrev_b64 v[98:99], 11, v[4:5]
	v_lshl_add_u64 v[22:23], s[24:25], 0, v[186:187]
	s_movk_i32 s2, 0x130
	v_lshl_add_u64 v[6:7], v[6:7], 0, v[98:99]
	v_mul_lo_u32 v138, v4, s2
	global_load_dwordx4 v[14:17], v[6:7], off
	v_lshl_add_u64 v[4:5], v[22:23], 0, v[96:97]
	v_mul_lo_u32 v137, v2, s2
	global_load_dwordx4 v[18:21], v[4:5], off
	v_lshl_add_u64 v[2:3], v[22:23], 0, v[98:99]
	global_load_dwordx4 v[22:25], v[2:3], off
	v_add3_u32 v26, 0, v137, v186
	s_mov_b32 s2, 0x20000
	v_add3_u32 v27, 0, v138, v186
	v_lshlrev_b32_e32 v180, 2, v135
	v_bfe_u32 v1, v134, 2, 2
	s_lshl_b32 s10, s17, 7
	v_or_b32_e32 v1, v180, v1
	v_or_b32_e32 v181, v101, v100
	s_mov_b32 s19, 0
	v_mul_u32_u24_e32 v182, 0x130, v1
	v_add_co_u32_e32 v28, vcc, s2, v8
	s_nop 1
	v_addc_co_u32_e32 v29, vcc, 0, v9, vcc
	v_add_co_u32_e32 v32, vcc, s2, v6
	global_load_dwordx4 v[28:31], v[28:29], off
	s_nop 0
	v_addc_co_u32_e32 v33, vcc, 0, v7, vcc
	v_add_co_u32_e32 v36, vcc, s2, v4
	global_load_dwordx4 v[32:35], v[32:33], off
	s_nop 0
	v_addc_co_u32_e32 v37, vcc, 0, v5, vcc
	v_add_co_u32_e32 v40, vcc, s2, v2
	global_load_dwordx4 v[36:39], v[36:37], off
	s_nop 0
	v_addc_co_u32_e32 v41, vcc, 0, v3, vcc
	global_load_dwordx4 v[40:43], v[40:41], off
	s_cmp_eq_u32 s6, 15
	s_waitcnt vmcnt(7)
	ds_write_b128 v26, v[10:13]
	s_waitcnt vmcnt(6)
	ds_write_b128 v27, v[14:17]
	s_waitcnt vmcnt(5)
	ds_write_b128 v26, v[18:21] offset:19456
	s_waitcnt vmcnt(4)
	ds_write_b128 v27, v[22:25] offset:19456
	s_waitcnt vmcnt(3)
	ds_write_b128 v26, v[28:31] offset:38912
	s_waitcnt vmcnt(2)
	ds_write_b128 v27, v[32:35] offset:38912
	s_waitcnt vmcnt(1)
	ds_write_b128 v26, v[36:39] offset:58368
	s_waitcnt vmcnt(0)
	ds_write_b128 v27, v[40:43] offset:58368
	v_mul_u32_u24_e32 v10, 0x130, v179
	v_add3_u32 v144, v0, v10, s10
	s_mov_b32 s10, 0
	s_waitcnt lgkmcnt(0)
	s_barrier
	s_cbranch_scc1 .LBB0_853
	v_add_co_u32_e32 v0, vcc, 0x40000, v8
	s_mov_b32 s11, 1
	s_nop 0
	v_addc_co_u32_e32 v1, vcc, 0, v9, vcc
	v_add_co_u32_e32 v6, vcc, 0x40000, v6
	s_lshl_b32 s19, s12, 1
	s_nop 0
	v_addc_co_u32_e32 v7, vcc, 0, v7, vcc
	global_load_dwordx4 v[80:83], v[0:1], off
	global_load_dwordx4 v[84:87], v[6:7], off
	v_add_co_u32_e32 v0, vcc, 0x40000, v4
	s_nop 1
	v_addc_co_u32_e32 v1, vcc, 0, v5, vcc
	v_add_co_u32_e32 v2, vcc, 0x40000, v2
	s_nop 1
	v_addc_co_u32_e32 v3, vcc, 0, v3, vcc
	global_load_dwordx4 v[88:91], v[0:1], off
	global_load_dwordx4 v[92:95], v[2:3], off
	v_add_u32_e32 v4, 0, v144
	ds_read_b128 v[0:3], v4
	ds_read_b128 v[32:35], v4 offset:32
	ds_read_b128 v[16:19], v4 offset:9728
	ds_read_b128 v[36:39], v4 offset:9760
	ds_read_b128 v[40:43], v4 offset:64
	ds_read_b128 v[44:47], v4 offset:96
	ds_read_b128 v[48:51], v4 offset:9792
	ds_read_b128 v[52:55], v4 offset:9824
	s_setprio 1
	s_waitcnt lgkmcnt(7)
	v_mfma_f32_32x32x16_bf16 v[0:15], v[0:3], v[172:175], 0
	s_waitcnt lgkmcnt(5)
	v_mfma_f32_32x32x16_bf16 v[16:31], v[16:19], v[172:175], 0
	v_mfma_f32_32x32x16_bf16 v[0:15], v[32:35], v[168:171], v[0:15]
	s_waitcnt lgkmcnt(4)
	v_mfma_f32_32x32x16_bf16 v[16:31], v[36:39], v[168:171], v[16:31]
	s_waitcnt lgkmcnt(3)
	v_mfma_f32_32x32x16_bf16 v[0:15], v[40:43], v[164:167], v[0:15]
	s_waitcnt lgkmcnt(1)
	v_mfma_f32_32x32x16_bf16 v[16:31], v[48:51], v[164:167], v[16:31]
	v_mfma_f32_32x32x16_bf16 v[0:15], v[44:47], v[160:163], v[0:15]
	s_waitcnt lgkmcnt(0)
; DI unsigned cvtpk(float lo, float hi) { f32x2_t v = {lo, hi}; bf16x2_t b = __builtin_convertvector(v, bf16x2_t); return __builtin_bit_cast(unsigned, b); }
; template <int NDVB, bool HAS_NEXT> DI void softmax_def(f32x16& sa0, f32x16& sa1, f32x16& sb0, f32x16& sb1, f32x16 (&O)[NDVB], float& muse, float& l, bool first, bf16x8 (&P)[4], bool check = true) {
;   float mx = 0.f;
;   if (check) mx = rowmax32(sa0, sa1);
;   if (check && (first || __any(mx > 8.f))) {
;     float dl = first ? mx : fmaxf(mx, 0.f);
;     if (mx < -1e29f) dl = 0.f;
;     const float alpha = __builtin_amdgcn_exp2f(-dl);
;     muse += dl; l *= alpha;
; #pragma unroll
;     for (int i = 0; i < 16; ++i) { sa0[i] -= dl; sa1[i] -= dl; }
;     if (HAS_NEXT) {
; #pragma unroll
;       for (int i = 0; i < 16; ++i) { sb0[i] -= dl; sb1[i] -= dl; }
;     }
; #pragma unroll
;     for (int d = 0; d < NDVB; ++d)
; #pragma unroll
;       for (int i = 0; i < 16; ++i) O[d][i] *= alpha;
;   }
;   float sum = 0.f;
; #pragma unroll
;   for (int i = 0; i < 16; ++i) { sa0[i] = __builtin_amdgcn_exp2f(sa0[i]); sum += sa0[i]; }
; #pragma unroll
;   for (int i = 0; i < 16; ++i) { sa1[i] = __builtin_amdgcn_exp2f(sa1[i]); sum += sa1[i]; }
;   l += sum;
;   u32x4 w;
;   w.x = cvtpk(sa0[0], sa0[1]); w.y = cvtpk(sa0[2], sa0[3]); w.z = cvtpk(sa0[4], sa0[5]); w.w = cvtpk(sa0[6], sa0[7]); P[0] = __builtin_bit_cast(bf16x8, w);
;   w.x = cvtpk(sa0[8], sa0[9]); w.y = cvtpk(sa0[10], sa0[11]); w.z = cvtpk(sa0[12], sa0[13]); w.w = cvtpk(sa0[14], sa0[15]); P[1] = __builtin_bit_cast(bf16x8, w);
;   w.x = cvtpk(sa1[0], sa1[1]); w.y = cvtpk(sa1[2], sa1[3]); w.z = cvtpk(sa1[4], sa1[5]); w.w = cvtpk(sa1[6], sa1[7]); P[2] = __builtin_bit_cast(bf16x8, w);
;   w.x = cvtpk(sa1[8], sa1[9]); w.y = cvtpk(sa1[10], sa1[11]); w.z = cvtpk(sa1[12], sa1[13]); w.w = cvtpk(sa1[14], sa1[15]); P[3] = __builtin_bit_cast(bf16x8, w);
	v_mfma_f32_32x32x16_bf16 v[16:31], v[52:55], v[160:163], v[16:31]
	s_setprio 0
	s_nop 8
	v_max_f32_e32 v32, v1, v1
	v_max_f32_e32 v33, v0, v0
	v_max_f32_e32 v32, v33, v32
	v_max3_f32 v33, v2, v3, v17
	v_max3_f32 v32, v32, v16, v18
	v_max3_f32 v32, v32, v19, v4
	v_max3_f32 v33, v33, v6, v7
	v_max3_f32 v32, v32, v5, v20
	v_max3_f32 v33, v33, v22, v23
	v_max3_f32 v32, v32, v21, v8
	v_max3_f32 v33, v33, v10, v11
	v_max3_f32 v32, v32, v9, v24
	v_max3_f32 v33, v33, v26, v27
	v_max3_f32 v32, v32, v25, v12
	v_max3_f32 v33, v33, v14, v15
	v_max3_f32 v32, v32, v13, v28
	v_max3_f32 v33, v33, v30, v31
	v_and_b32_e32 v34, 64, v202
	v_max3_f32 v32, v32, v29, v33
	v_xor_b32_e32 v33, 32, v202
	v_add_u32_e32 v34, 64, v34
	v_cmp_lt_i32_e32 vcc, v33, v34
	v_add3_u32 v212, v181, v182, 0
	s_nop 0
	v_cndmask_b32_e32 v33, v202, v33, vcc
	v_lshlrev_b32_e32 v139, 2, v33
	ds_bpermute_b32 v33, v139, v32
	s_waitcnt lgkmcnt(0)
	v_max_f32_e32 v33, v33, v33
	v_max_f32_e32 v32, v32, v33
	v_cmp_ngt_f32_e32 vcc, s85, v32
	s_nop 1
	v_cndmask_b32_e32 v145, 0, v32, vcc
	v_exp_f32_e64 v32, -v145
	v_sub_f32_e32 v16, v16, v145
	v_sub_f32_e32 v17, v17, v145
	v_sub_f32_e32 v18, v18, v145
	v_sub_f32_e32 v19, v19, v145
	v_mul_f32_e32 v64, 0, v32
	v_exp_f32_e32 v188, v16
	v_exp_f32_e32 v189, v17
	v_exp_f32_e32 v190, v18
	v_exp_f32_e32 v191, v19
	ds_read_b64_tr_b16 v[16:17], v212 offset:19456
	ds_read_b64_tr_b16 v[32:33], v212 offset:19520
	ds_read_b64_tr_b16 v[48:49], v212 offset:19584
	ds_read_b64_tr_b16 v[114:115], v212 offset:19648
	ds_read_b64_tr_b16 v[18:19], v212 offset:21888
	ds_read_b64_tr_b16 v[34:35], v212 offset:21952
	ds_read_b64_tr_b16 v[50:51], v212 offset:22016
	ds_read_b64_tr_b16 v[116:117], v212 offset:22080
	ds_read_b64_tr_b16 v[118:119], v212 offset:24320
	ds_read_b64_tr_b16 v[122:123], v212 offset:24384
	ds_read_b64_tr_b16 v[126:127], v212 offset:24448
	ds_read_b64_tr_b16 v[130:131], v212 offset:24512
	ds_read_b64_tr_b16 v[120:121], v212 offset:26752
	ds_read_b64_tr_b16 v[124:125], v212 offset:26816
	ds_read_b64_tr_b16 v[128:129], v212 offset:26880
	ds_read_b64_tr_b16 v[132:133], v212 offset:26944
	v_sub_f32_e32 v0, v0, v145
	v_sub_f32_e32 v1, v1, v145
	v_sub_f32_e32 v2, v2, v145
	v_sub_f32_e32 v3, v3, v145
	v_sub_f32_e32 v20, v20, v145
	v_sub_f32_e32 v21, v21, v145
	v_sub_f32_e32 v22, v22, v145
	v_sub_f32_e32 v23, v23, v145
	v_sub_f32_e32 v24, v24, v145
	v_sub_f32_e32 v25, v25, v145
	v_sub_f32_e32 v26, v26, v145
	v_sub_f32_e32 v27, v27, v145
	v_sub_f32_e32 v28, v28, v145
	v_sub_f32_e32 v29, v29, v145
	v_sub_f32_e32 v30, v30, v145
	v_sub_f32_e32 v31, v31, v145
	v_sub_f32_e32 v4, v4, v145
	v_sub_f32_e32 v5, v5, v145
	v_sub_f32_e32 v6, v6, v145
	v_sub_f32_e32 v7, v7, v145
	v_sub_f32_e32 v8, v8, v145
	v_sub_f32_e32 v9, v9, v145
	v_sub_f32_e32 v10, v10, v145
	v_sub_f32_e32 v11, v11, v145
	v_sub_f32_e32 v12, v12, v145
	v_sub_f32_e32 v13, v13, v145
	v_sub_f32_e32 v14, v14, v145
	v_sub_f32_e32 v15, v15, v145
	v_exp_f32_e32 v146, v0
	v_exp_f32_e32 v147, v1
	v_exp_f32_e32 v148, v2
	v_exp_f32_e32 v149, v3
	v_exp_f32_e32 v150, v4
	v_exp_f32_e32 v151, v5
	v_exp_f32_e32 v152, v6
	v_exp_f32_e32 v153, v7
	v_exp_f32_e32 v154, v8
	v_exp_f32_e32 v155, v9
	v_exp_f32_e32 v156, v10
	v_exp_f32_e32 v157, v11
	v_exp_f32_e32 v158, v12
	v_exp_f32_e32 v159, v13
	v_exp_f32_e32 v176, v14
	v_exp_f32_e32 v177, v15
	v_exp_f32_e32 v192, v20
	v_exp_f32_e32 v193, v21
	v_exp_f32_e32 v194, v22
	v_exp_f32_e32 v195, v23
	v_exp_f32_e32 v196, v24
	v_exp_f32_e32 v197, v25
	v_exp_f32_e32 v198, v26
	v_exp_f32_e32 v199, v27
	v_exp_f32_e32 v208, v28
	v_exp_f32_e32 v209, v29
	v_exp_f32_e32 v210, v30
	v_exp_f32_e32 v211, v31
	v_mov_b32_e32 v65, v64
	v_mov_b32_e32 v66, v64
	v_mov_b32_e32 v67, v64
	v_mov_b32_e32 v68, v64
	v_mov_b32_e32 v69, v64
	v_mov_b32_e32 v70, v64
	v_mov_b32_e32 v71, v64
	v_mov_b32_e32 v72, v64
	v_mov_b32_e32 v73, v64
	v_mov_b32_e32 v74, v64
	v_mov_b32_e32 v75, v64
	v_mov_b32_e32 v76, v64
	v_mov_b32_e32 v77, v64
	v_mov_b32_e32 v78, v64
	v_mov_b32_e32 v79, v64
	v_cvt_pk_bf16_f32 v140, v146, v147
	v_cvt_pk_bf16_f32 v141, v148, v149
	v_cmp_neq_f32_e32 vcc, 0, v145
	v_cvt_pk_bf16_f32 v102, v196, v197
	v_cvt_pk_bf16_f32 v103, v198, v199
	v_cvt_pk_bf16_f32 v104, v208, v209
	v_cvt_pk_bf16_f32 v105, v210, v211
	v_cvt_pk_bf16_f32 v106, v188, v189
	v_cvt_pk_bf16_f32 v107, v190, v191
	v_cvt_pk_bf16_f32 v108, v192, v193
	v_cvt_pk_bf16_f32 v109, v194, v195
	v_cvt_pk_bf16_f32 v110, v154, v155
	v_cvt_pk_bf16_f32 v111, v156, v157
	v_cvt_pk_bf16_f32 v112, v158, v159
	v_cvt_pk_bf16_f32 v113, v176, v177
	v_cvt_pk_bf16_f32 v142, v150, v151
	v_cvt_pk_bf16_f32 v143, v152, v153
	s_setprio 1
	s_waitcnt lgkmcnt(11)
	v_mfma_f32_32x32x16_bf16 v[0:15], v[16:19], v[140:143], v[64:79]
	s_waitcnt lgkmcnt(10)
	v_mfma_f32_32x32x16_bf16 v[16:31], v[32:35], v[140:143], v[64:79]
	s_waitcnt lgkmcnt(9)
	v_mfma_f32_32x32x16_bf16 v[32:47], v[48:51], v[140:143], v[64:79]
	v_mov_b64_e32 v[48:49], v[64:65]
	v_mov_b64_e32 v[50:51], v[66:67]
	v_mov_b64_e32 v[52:53], v[68:69]
	v_mov_b64_e32 v[54:55], v[70:71]
	v_mov_b64_e32 v[56:57], v[72:73]
	v_mov_b64_e32 v[58:59], v[74:75]
	v_mov_b64_e32 v[60:61], v[76:77]
	v_mov_b64_e32 v[62:63], v[78:79]
	s_waitcnt lgkmcnt(8)
; #define LAS __attribute__((address_space(3)))
; #define MFMA32(a, b, c) __builtin_amdgcn_mfma_f32_32x32x16_bf16((a), (b), (c), 0, 0, 0)
; #define SBAR() __builtin_amdgcn_sched_barrier(0)
; DI s16x4 trrd(const lds8* p) { typedef short v4i16_t __attribute__((ext_vector_type(4))); return __builtin_bit_cast(s16x4, __builtin_amdgcn_ds_read_tr16_b64_v4i16((LAS v4i16_t*)p)); }
; template <int VSTR, int NDVB> DI void pv64(f32x16 (&O)[NDVB], const lds8* vp, const bf16x8 (&P)[4]) {
;   bf16x8 f[2][NDVB];
; #pragma unroll
;   for (int d = 0; d < NDVB; ++d) { const s16x4 lo = trrd(vp + d * 64), hi = trrd(vp + 8 * VSTR + d * 64); f[0][d] = __builtin_shufflevector(lo, hi, 0, 1, 2, 3, 4, 5, 6, 7); }
; #pragma unroll
;   for (int kk = 0; kk < 4; ++kk) {
;     if (kk < 3) {
; #pragma unroll
;       for (int d = 0; d < NDVB; ++d) { const s16x4 lo = trrd(vp + (16 * (kk + 1)) * VSTR + d * 64), hi = trrd(vp + (16 * (kk + 1) + 8) * VSTR + d * 64);
;         f[(kk + 1) & 1][d] = __builtin_shufflevector(lo, hi, 0, 1, 2, 3, 4, 5, 6, 7); }
;     }
;     SBAR();
;     __builtin_amdgcn_s_setprio(1);
; #pragma unroll
;     for (int d = 0; d < NDVB; ++d) O[d] = MFMA32(f[kk & 1][d], P[kk], O[d]);
;     __builtin_amdgcn_s_setprio(0);
;     SBAR();
;   }
; }
; template <bool LOAD2, bool MASK>
; DI void da_step(lds8* lds, const DaCtx& cx, int t, const bf16x8 (&q)[4], f32x16 (&O)[4], float& muse, float& l, f32x16& negm) {
;     ...
;     const float mprev = muse;
;     softmax_def<4, false>(sa0, sa1, du0, du1, O, muse, l, t == 0, P, MASK || (t & 1) == 0);
;     if (__any(muse != mprev)) {
; #pragma unroll
;       for (int i = 0; i < 16; ++i) negm[i] = -muse;
;     }
;     pv64<DA_KSTR, 4>(O, lds + st * DA_STAGE + cx.voff, P);
;   }
;   if (LOAD2) { lds8* b = lds + stn2 * DA_STAGE;
;     *(LAS u32x4*)(b + cx.sr0 * DA_KSTR + cx.sc0 * 16) = kr0; *(LAS u32x4*)(b + cx.sr1 * DA_KSTR + cx.sc1 * 16) = kr1;
;     *(LAS u32x4*)(b + 64 * DA_KSTR + cx.sr0 * DA_KSTR + cx.sc0 * 16) = vr0; *(LAS u32x4*)(b + 64 * DA_KSTR + cx.sr1 * DA_KSTR + cx.sc1 * 16) = vr1;
;     __syncthreads(); }
	s_nop 0
	v_mfma_f32_32x32x16_bf16 v[48:63], v[114:117], v[140:143], v[48:63]
	s_setprio 0
	ds_read_b64_tr_b16 v[66:67], v212 offset:29184
	ds_read_b64_tr_b16 v[70:71], v212 offset:29248
	ds_read_b64_tr_b16 v[74:75], v212 offset:29312
	ds_read_b64_tr_b16 v[114:115], v212 offset:29376
	ds_read_b64_tr_b16 v[68:69], v212 offset:31616
	ds_read_b64_tr_b16 v[72:73], v212 offset:31680
	ds_read_b64_tr_b16 v[76:77], v212 offset:31744
	ds_read_b64_tr_b16 v[116:117], v212 offset:31808
	s_setprio 1
	s_waitcnt lgkmcnt(11)
	v_mfma_f32_32x32x16_bf16 v[0:15], v[118:121], v[110:113], v[0:15]
	s_waitcnt lgkmcnt(10)
	v_mfma_f32_32x32x16_bf16 v[16:31], v[122:125], v[110:113], v[16:31]
	s_waitcnt lgkmcnt(9)
	v_mfma_f32_32x32x16_bf16 v[32:47], v[126:129], v[110:113], v[32:47]
	s_waitcnt lgkmcnt(8)
	v_mfma_f32_32x32x16_bf16 v[48:63], v[130:133], v[110:113], v[48:63]
	s_setprio 0
	ds_read_b64_tr_b16 v[110:111], v212 offset:34048
	ds_read_b64_tr_b16 v[118:119], v212 offset:34112
	ds_read_b64_tr_b16 v[122:123], v212 offset:34176
	ds_read_b64_tr_b16 v[126:127], v212 offset:34240
	ds_read_b64_tr_b16 v[112:113], v212 offset:36480
	ds_read_b64_tr_b16 v[120:121], v212 offset:36544
	ds_read_b64_tr_b16 v[124:125], v212 offset:36608
	ds_read_b64_tr_b16 v[128:129], v212 offset:36672
	s_setprio 1
	s_waitcnt lgkmcnt(11)
	v_mfma_f32_32x32x16_bf16 v[0:15], v[66:69], v[106:109], v[0:15]
	s_waitcnt lgkmcnt(10)
	v_mfma_f32_32x32x16_bf16 v[16:31], v[70:73], v[106:109], v[16:31]
	s_waitcnt lgkmcnt(9)
	v_mfma_f32_32x32x16_bf16 v[32:47], v[74:77], v[106:109], v[32:47]
	s_waitcnt lgkmcnt(8)
	v_mfma_f32_32x32x16_bf16 v[48:63], v[114:117], v[106:109], v[48:63]
	s_setprio 0
	s_setprio 1
	s_waitcnt lgkmcnt(3)
	v_mfma_f32_32x32x16_bf16 v[0:15], v[110:113], v[102:105], v[0:15]
	s_waitcnt lgkmcnt(2)
	v_mfma_f32_32x32x16_bf16 v[16:31], v[118:121], v[102:105], v[16:31]
	s_waitcnt lgkmcnt(1)
	v_mfma_f32_32x32x16_bf16 v[32:47], v[122:125], v[102:105], v[32:47]
	s_waitcnt lgkmcnt(0)
	v_mfma_f32_32x32x16_bf16 v[48:63], v[126:129], v[102:105], v[48:63]
	s_setprio 0
	v_readlane_b32 s2, v255, 5
	v_mov_b32_e32 v67, v187
	s_cmp_lg_u64 vcc, 0
	v_add3_u32 v65, s2, v137, v186
	s_waitcnt vmcnt(3)
	ds_write_b128 v65, v[80:83]
	v_add3_u32 v65, s2, v138, v186
	v_readlane_b32 s2, v255, 6
	s_waitcnt vmcnt(2)
	ds_write_b128 v65, v[84:87]
	s_cselect_b64 s[12:13], -1, 0
	v_add3_u32 v65, s2, v137, v186
	s_waitcnt vmcnt(1)
	ds_write_b128 v65, v[88:91]
	v_add3_u32 v65, s2, v138, v186
	s_waitcnt vmcnt(0)
	ds_write_b128 v65, v[92:95]
	v_add_f32_e32 v65, 0, v146
	v_add_f32_e32 v65, v147, v65
	v_add_f32_e32 v65, v148, v65
	v_add_f32_e32 v65, v149, v65
	v_add_f32_e32 v65, v150, v65
	v_add_f32_e32 v65, v151, v65
	v_add_f32_e32 v65, v152, v65
	v_add_f32_e32 v65, v153, v65
	v_add_f32_e32 v65, v154, v65
	v_add_f32_e32 v65, v155, v65
	v_add_f32_e32 v65, v156, v65
	v_add_f32_e32 v65, v157, v65
	v_add_f32_e32 v65, v158, v65
	v_add_f32_e32 v65, v159, v65
	v_add_f32_e32 v65, v176, v65
	v_add_f32_e32 v65, v177, v65
	v_add_f32_e32 v65, v188, v65
	v_add_f32_e32 v65, v189, v65
	v_add_f32_e32 v65, v190, v65
	v_add_f32_e32 v65, v191, v65
	v_add_f32_e32 v65, v192, v65
	v_add_f32_e32 v65, v193, v65
	v_add_f32_e32 v65, v194, v65
	v_add_f32_e32 v65, v195, v65
	v_add_f32_e32 v65, v196, v65
	v_add_f32_e32 v65, v197, v65
	v_add_f32_e32 v65, v198, v65
	v_add_f32_e32 v65, v199, v65
	v_add_f32_e32 v65, v208, v65
	v_add_f32_e32 v65, v209, v65
	v_add_f32_e32 v65, v210, v65
	v_add_f32_e32 v66, v211, v65
	v_mov_b32_e32 v65, v145
	v_pk_add_f32 v[176:177], v[64:65], v[66:67]
	s_lshl_b32 s6, s6, 1
	v_cndmask_b32_e64 v64, 0, -v177, s[12:13]
	s_lshl_b32 s12, s20, 19
	s_and_b32 s13, s20, 7
	s_sub_i32 s6, 29, s6
	s_and_b32 s12, s12, 0x3c00000
	s_lshl_b32 s13, s13, 8
	s_add_u32 s13, s56, s13
	s_addc_u32 s20, s57, 0
	v_add_u32_e32 v80, v182, v100
	v_readlane_b32 s2, v255, 7
	s_add_u32 s12, s13, s12
	s_addc_u32 s13, s20, 0
	v_add3_u32 v140, v80, v101, s2
	v_readlane_b32 s2, v255, 8
	v_mov_b32_e32 v65, v64
	v_mov_b32_e32 v66, v64
	v_mov_b32_e32 v67, v64
	v_mov_b32_e32 v68, v64
	v_mov_b32_e32 v69, v64
	v_mov_b32_e32 v70, v64
	v_mov_b32_e32 v71, v64
	v_mov_b32_e32 v72, v64
	v_mov_b32_e32 v73, v64
	v_mov_b32_e32 v74, v64
	v_mov_b32_e32 v75, v64
	v_mov_b32_e32 v76, v64
	v_mov_b32_e32 v77, v64
	v_mov_b32_e32 v78, v64
	v_mov_b32_e32 v79, v64
	v_lshl_add_u64 v[130:131], s[12:13], 0, v[96:97]
	v_lshl_add_u64 v[132:133], s[12:13], 0, v[98:99]
	v_add_u32_e32 v141, s2, v144
	v_bfe_u32 v216, v134, 2, 2
	v_sub_u32_e32 v216, v216, v135
	v_mul_i32_i24_e32 v216, 0x390, v216
	v_add_u32_e32 v140, v140, v216
	v_and_b32_e32 v216, 16, v179
	v_and_b32_e32 v217, 3, v179
	v_lshl_add_u32 v216, v217, 2, v216
	v_bfe_u32 v217, v179, 3, 1
	v_lshl_add_u32 v216, v217, 1, v216
	v_bfe_u32 v217, v179, 2, 1
	v_add_u32_e32 v216, v216, v217
	v_sub_u32_e32 v216, v216, v179
	v_mul_i32_i24_e32 v216, 0x130, v216
	v_add_u32_e32 v141, v141, v216
	s_mov_b32 s12, 0
	s_waitcnt lgkmcnt(0)
	s_barrier

; #define MFMA32(a, b, c) __builtin_amdgcn_mfma_f32_32x32x16_bf16((a), (b), (c), 0, 0, 0)
; template <int VSTR, int NDVB> DI void pv64(f32x16 (&O)[NDVB], const lds8* vp, const bf16x8 (&P)[4]) {
;   bf16x8 f[2][NDVB];
; #pragma unroll
;   for (int d = 0; d < NDVB; ++d) { const s16x4 lo = trrd(vp + d * 64), hi = trrd(vp + 8 * VSTR + d * 64); f[0][d] = __builtin_shufflevector(lo, hi, 0, 1, 2, 3, 4, 5, 6, 7); }
; #pragma unroll
;   for (int kk = 0; kk < 4; ++kk) {
;     if (kk < 3) {
; #pragma unroll
;       for (int d = 0; d < NDVB; ++d) { const s16x4 lo = trrd(vp + (16 * (kk + 1)) * VSTR + d * 64), hi = trrd(vp + (16 * (kk + 1) + 8) * VSTR + d * 64);
;         f[(kk + 1) & 1][d] = __builtin_shufflevector(lo, hi, 0, 1, 2, 3, 4, 5, 6, 7); }
;     }
;     SBAR();
;     __builtin_amdgcn_s_setprio(1);
; #pragma unroll
;     for (int d = 0; d < NDVB; ++d) O[d] = MFMA32(f[kk & 1][d], P[kk], O[d]);
;     __builtin_amdgcn_s_setprio(0);
;     SBAR();
;   }
; }
; template <int NDVB, bool HAS_NEXT> DI void softmax_def(f32x16& sa0, f32x16& sa1, f32x16& sb0, f32x16& sb1, f32x16 (&O)[NDVB], float& muse, float& l, bool first, bf16x8 (&P)[4], bool check = true) {
;   float mx = 0.f;
;   if (check) mx = rowmax32(sa0, sa1);
;   if (check && (first || __any(mx > 8.f))) {
;     float dl = first ? mx : fmaxf(mx, 0.f);
;     if (mx < -1e29f) dl = 0.f;
;     const float alpha = __builtin_amdgcn_exp2f(-dl);
;     muse += dl; l *= alpha;
; #pragma unroll
;     for (int i = 0; i < 16; ++i) { sa0[i] -= dl; sa1[i] -= dl; }
;     if (HAS_NEXT) {
; #pragma unroll
;       for (int i = 0; i < 16; ++i) { sb0[i] -= dl; sb1[i] -= dl; }
;     }
; #pragma unroll
;     for (int d = 0; d < NDVB; ++d)
; #pragma unroll
;       for (int i = 0; i < 16; ++i) O[d][i] *= alpha;
;   }
;   float sum = 0.f;
; #pragma unroll
;   for (int i = 0; i < 16; ++i) { sa0[i] = __builtin_amdgcn_exp2f(sa0[i]); sum += sa0[i]; }
; #pragma unroll
;   for (int i = 0; i < 16; ++i) { sa1[i] = __builtin_amdgcn_exp2f(sa1[i]); sum += sa1[i]; }
;   l += sum;
;   u32x4 w;
;   w.x = cvtpk(sa0[0], sa0[1]); w.y = cvtpk(sa0[2], sa0[3]); w.z = cvtpk(sa0[4], sa0[5]); w.w = cvtpk(sa0[6], sa0[7]); P[0] = __builtin_bit_cast(bf16x8, w);
;   w.x = cvtpk(sa0[8], sa0[9]); w.y = cvtpk(sa0[10], sa0[11]); w.z = cvtpk(sa0[12], sa0[13]); w.w = cvtpk(sa0[14], sa0[15]); P[1] = __builtin_bit_cast(bf16x8, w);
.LBB0_851:
	s_nop 3
	v_add_u32_e32 v145, s20, v140
	v_add_u32_e32 v145, 0xffffbcc0, v145
	ds_read_b64_tr_b16 v[232:233], v145 offset:0
	ds_read_b64_tr_b16 v[234:235], v145 offset:608
	ds_read_b64_tr_b16 v[236:237], v145 offset:64
	ds_read_b64_tr_b16 v[238:239], v145 offset:672
	ds_read_b64_tr_b16 v[240:241], v145 offset:128
	ds_read_b64_tr_b16 v[242:243], v145 offset:736
	ds_read_b64_tr_b16 v[244:245], v145 offset:192
	ds_read_b64_tr_b16 v[246:247], v145 offset:800
	ds_read_b64_tr_b16 v[146:147], v145 offset:4864
	ds_read_b64_tr_b16 v[148:149], v145 offset:5472
	ds_read_b64_tr_b16 v[150:151], v145 offset:4928
	ds_read_b64_tr_b16 v[152:153], v145 offset:5536
	ds_read_b64_tr_b16 v[154:155], v145 offset:4992
	ds_read_b64_tr_b16 v[156:157], v145 offset:5600
	ds_read_b64_tr_b16 v[192:193], v145 offset:5056
	ds_read_b64_tr_b16 v[194:195], v145 offset:5664
	s_mul_i32 s21, s21, 3
	s_add_i32 s21, s21, -1
	v_exp_f32_e32 v96, v96
	v_exp_f32_e32 v97, v97
	v_exp_f32_e32 v98, v98
	v_exp_f32_e32 v99, v99
	v_exp_f32_e32 v100, v100
	v_exp_f32_e32 v101, v101
	v_exp_f32_e32 v102, v102
	v_exp_f32_e32 v103, v103
	v_cvt_pk_bf16_f32 v216, v96, v97
	v_cvt_pk_bf16_f32 v217, v98, v99
	v_cvt_pk_bf16_f32 v218, v100, v101
	v_cvt_pk_bf16_f32 v219, v102, v103
	v_readfirstlane_b32 s22, v200
	s_nop 1
	s_bitcmp1_b32 s22, 8
	s_cbranch_scc0 .Lda_nobar_b
	s_barrier
.Lda_nobar_b:
	s_setprio 1
	s_waitcnt lgkmcnt(14)
	v_mfma_f32_32x32x16_bf16 v[0:15], v[232:235], v[216:219], v[0:15]
	v_exp_f32_e32 v104, v104
	v_exp_f32_e32 v105, v105
	v_exp_f32_e32 v106, v106
	s_waitcnt lgkmcnt(12)
	v_mfma_f32_32x32x16_bf16 v[16:31], v[236:239], v[216:219], v[16:31]
	v_exp_f32_e32 v107, v107
	v_exp_f32_e32 v108, v108
	v_exp_f32_e32 v109, v109
	s_waitcnt lgkmcnt(10)
	v_mfma_f32_32x32x16_bf16 v[32:47], v[240:243], v[216:219], v[32:47]
	v_exp_f32_e32 v110, v110
	v_exp_f32_e32 v111, v111
	v_add_f32_e32 v142, 0, v96
	v_add_f32_e32 v142, v97, v142
	s_waitcnt lgkmcnt(8)
	v_mfma_f32_32x32x16_bf16 v[48:63], v[244:247], v[216:219], v[48:63]
	v_cvt_pk_bf16_f32 v220, v104, v105
	v_cvt_pk_bf16_f32 v221, v106, v107
	v_cvt_pk_bf16_f32 v222, v108, v109
	v_cvt_pk_bf16_f32 v223, v110, v111
	v_add_f32_e32 v142, v98, v142
	v_add_f32_e32 v142, v99, v142
	s_setprio 0
	ds_read_b64_tr_b16 v[232:233], v145 offset:9728
	ds_read_b64_tr_b16 v[234:235], v145 offset:10336
	ds_read_b64_tr_b16 v[236:237], v145 offset:9792
	ds_read_b64_tr_b16 v[238:239], v145 offset:10400
	ds_read_b64_tr_b16 v[240:241], v145 offset:9856
	ds_read_b64_tr_b16 v[242:243], v145 offset:10464
	ds_read_b64_tr_b16 v[244:245], v145 offset:9920
	ds_read_b64_tr_b16 v[246:247], v145 offset:10528
	s_setprio 1
	s_waitcnt lgkmcnt(14)
	v_mfma_f32_32x32x16_bf16 v[0:15], v[146:149], v[220:223], v[0:15]
	v_exp_f32_e32 v80, v80
	v_exp_f32_e32 v81, v81
	v_add_f32_e32 v142, v100, v142
	v_add_f32_e32 v142, v101, v142
	s_waitcnt lgkmcnt(12)
	v_mfma_f32_32x32x16_bf16 v[16:31], v[150:153], v[220:223], v[16:31]
	v_exp_f32_e32 v82, v82
	v_exp_f32_e32 v83, v83
	v_add_f32_e32 v142, v102, v142
	v_add_f32_e32 v142, v103, v142
	s_waitcnt lgkmcnt(10)
	v_mfma_f32_32x32x16_bf16 v[32:47], v[154:157], v[220:223], v[32:47]
	v_exp_f32_e32 v84, v84
	v_exp_f32_e32 v85, v85
	v_add_f32_e32 v142, v104, v142
	v_add_f32_e32 v142, v105, v142
	s_waitcnt lgkmcnt(8)
	v_mfma_f32_32x32x16_bf16 v[48:63], v[192:195], v[220:223], v[48:63]
	v_exp_f32_e32 v86, v86
	v_exp_f32_e32 v87, v87
	v_add_f32_e32 v142, v106, v142
	v_add_f32_e32 v142, v107, v142
	v_add_f32_e32 v142, v108, v142
	v_add_f32_e32 v142, v109, v142
	v_add_f32_e32 v142, v110, v142
	v_add_f32_e32 v142, v111, v142
	v_cvt_pk_bf16_f32 v224, v80, v81
	v_cvt_pk_bf16_f32 v225, v82, v83
	v_cvt_pk_bf16_f32 v226, v84, v85
	v_cvt_pk_bf16_f32 v227, v86, v87
	s_setprio 0
	ds_read_b64_tr_b16 v[250:251], v145 offset:15264
	ds_read_b64_tr_b16 v[108:109], v145 offset:14720
	ds_read_b64_tr_b16 v[110:111], v145 offset:15328
	ds_read_b64_tr_b16 v[146:147], v145 offset:14784
	ds_read_b64_tr_b16 v[150:151], v145 offset:14592
	ds_read_b64_tr_b16 v[152:153], v145 offset:15200
	ds_read_b64_tr_b16 v[248:249], v145 offset:14656
	ds_read_b64_tr_b16 v[148:149], v145 offset:15392
	s_setprio 1
	s_waitcnt lgkmcnt(14)
	v_mfma_f32_32x32x16_bf16 v[0:15], v[232:235], v[224:227], v[0:15]
	v_exp_f32_e32 v88, v88
	v_exp_f32_e32 v89, v89
	v_add_f32_e32 v142, v80, v142
	v_add_f32_e32 v142, v81, v142
	s_waitcnt lgkmcnt(12)
	v_mfma_f32_32x32x16_bf16 v[16:31], v[236:239], v[224:227], v[16:31]
	v_exp_f32_e32 v90, v90
	v_exp_f32_e32 v91, v91
	v_add_f32_e32 v142, v82, v142
	v_add_f32_e32 v142, v83, v142
	s_waitcnt lgkmcnt(10)
	v_mfma_f32_32x32x16_bf16 v[32:47], v[240:243], v[224:227], v[32:47]
	v_exp_f32_e32 v92, v92
	v_exp_f32_e32 v93, v93
	v_add_f32_e32 v142, v84, v142
	v_add_f32_e32 v142, v85, v142
	s_waitcnt lgkmcnt(8)
	v_mfma_f32_32x32x16_bf16 v[48:63], v[244:247], v[224:227], v[48:63]
	v_exp_f32_e32 v94, v94
	v_exp_f32_e32 v95, v95
	v_add_f32_e32 v142, v86, v142
	v_add_f32_e32 v142, v87, v142
	v_cvt_pk_bf16_f32 v228, v88, v89
	v_cvt_pk_bf16_f32 v229, v90, v91
	v_cvt_pk_bf16_f32 v230, v92, v93
	v_cvt_pk_bf16_f32 v231, v94, v95
	s_setprio 0
	s_setprio 1
	s_waitcnt lgkmcnt(2)
	v_mfma_f32_32x32x16_bf16 v[0:15], v[150:153], v[228:231], v[0:15]
	v_add_f32_e32 v142, v88, v142
	v_add_f32_e32 v142, v89, v142
	v_add_f32_e32 v142, v90, v142
	v_add_f32_e32 v142, v91, v142
	s_waitcnt lgkmcnt(1)
	v_mfma_f32_32x32x16_bf16 v[16:31], v[248:251], v[228:231], v[16:31]
	v_add_f32_e32 v142, v92, v142
	v_add_f32_e32 v142, v93, v142
	v_add_f32_e32 v142, v94, v142
	v_add_f32_e32 v142, v95, v142
	v_mfma_f32_32x32x16_bf16 v[32:47], v[108:111], v[228:231], v[32:47]
	v_add_f32_e32 v176, v128, v142
	v_cmp_neq_f32_e32 vcc, v129, v177
	v_add_u32_e32 v140, 0x9800, v140
	v_add_u32_e32 v141, 0x9800, v141
	v_lshl_add_u64 v[130:131], v[130:131], 0, s[90:91]
	v_lshl_add_u64 v[132:133], v[132:133], 0, s[90:91]
	s_waitcnt lgkmcnt(0)
	v_mfma_f32_32x32x16_bf16 v[48:63], v[146:149], v[228:231], v[48:63]
	s_mov_b32 s22, 0x80000000
	s_cmp_eq_u64 vcc, 0
	s_cbranch_scc1 .Lda_negm_same
	v_xor_b32_e32 v79, s22, v129
	v_xor_b32_e32 v78, s22, v129
	v_xor_b32_e32 v77, s22, v129
	v_xor_b32_e32 v76, s22, v129
	v_xor_b32_e32 v75, s22, v129
	v_xor_b32_e32 v74, s22, v129
	v_xor_b32_e32 v73, s22, v129
	v_xor_b32_e32 v72, s22, v129
	v_xor_b32_e32 v71, s22, v129
	v_xor_b32_e32 v70, s22, v129
	v_xor_b32_e32 v69, s22, v129
	v_xor_b32_e32 v68, s22, v129
	v_xor_b32_e32 v67, s22, v129
	v_xor_b32_e32 v66, s22, v129
	v_xor_b32_e32 v65, s22, v129
	v_xor_b32_e32 v64, s22, v129
